# GLA: rk/rl prefetch one full chunk ahead, rq at chunk end, O RMW loads in two batches, relaxed counted vmcnt, LDS-batched steps 4/5
# speedup vs baseline: 1.0048x; 1.0048x over previous
; __device__ __forceinline__ unsigned cvt_pk_bf16(float lo, float hi) { const f32x2 v = {lo, hi}; const bf16x2_t b = __builtin_convertvector(v, bf16x2_t); return __builtin_bit_cast(unsigned, b); }
; __device__ __forceinline__ float bflo(unsigned w) { return __uint_as_float(w << 16); }
; __device__ __forceinline__ float bfhi(unsigned w) { return __uint_as_float(w & 0xffff0000u); }
; template <bool PASS2>
; __device__ __forceinline__ void gla_pass(LAS unsigned char* lds, const Params& p, int layer) {
;     ...
;             { const float* Wc = (dir ? p.wdu_b : p.wdu_f) + (size_t)layer * 16 * 512 + h * 128 + wid * 16 + fr;
;               float wv[8]; unsigned h1[4], h2[4];
; #pragma unroll
;               for (int j = 0; j < 8; ++j) wv[j] = Wc[((fq & 1) * 8 + j) * 512];
; #pragma unroll
;               for (int jp = 0; jp < 4; ++jp) { const float a = wv[2 * jp], bq = wv[2 * jp + 1]; const unsigned hi = cvt_pk_bf16(a, bq);
;                   const unsigned lo = cvt_pk_bf16(a - bflo(hi), bq - bfhi(hi)); h1[jp] = hi; h2[jp] = fq < 2 ? lo : 0u; }
;               wB1 = __builtin_bit_cast(bf16x8, (u32x4){h1[0], h1[1], h1[2], h1[3]}); wB2 = __builtin_bit_cast(bf16x8, (u32x4){h2[0], h2[1], h2[2], h2[3]});
;               biasx = (dir ? p.bd_b : p.bd_f)[layer * 512 + h * 128 + wid * 16 + fr]; }
;             f32x4 accS[8][2];
; #pragma unroll
;             for (int m8 = 0; m8 < 8; ++m8)
; #pragma unroll
;                 for (int n = 0; n < 2; ++n) accS[m8][n] = (f32x4){0.f, 0.f, 0.f, 0.f};
;             float gtot0 = 0.f, gtot1 = 0.f;
;             u32x4 rk[2], rq[2], rv[4]; u32x4 rl = (u32x4){0u, 0u, 0u, 0u};
;     ...
;             GLA_ISSUE(0);
.LBB0_446:
	s_and_b64 s[4:5], s[14:15], exec
	s_cselect_b32 s4, 24, 40
	v_readlane_b32 s34, v254, 23
	v_readlane_b32 s35, v254, 24
	s_add_u32 s4, s34, s4
	s_addc_u32 s5, s35, 0
	s_load_dwordx2 s[4:5], s[4:5], 0x0
	v_mov_b32_e32 v135, v147
	s_waitcnt lgkmcnt(0)
	s_add_u32 s4, s4, s88
	s_addc_u32 s5, s5, s89
	s_add_u32 s4, s4, s94
	s_addc_u32 s5, s5, 0
	s_add_u32 s4, s4, s76
	s_addc_u32 s5, s5, s77
	v_lshl_add_u64 v[0:1], s[4:5], 0, v[146:147]
	v_lshl_add_u64 v[0:1], v[0:1], 0, v[134:135]
	s_movk_i32 s4, 0x1000
	v_add_co_u32_e32 v2, vcc, s4, v0
	s_movk_i32 s4, 0x2000
	s_nop 0
	v_addc_co_u32_e32 v3, vcc, 0, v1, vcc
	v_add_co_u32_e32 v4, vcc, s4, v0
	s_movk_i32 s4, 0x3000
	s_nop 0
	v_addc_co_u32_e32 v5, vcc, 0, v1, vcc
	global_load_dword v14, v[4:5], off offset:-4096
	global_load_dword v18, v[4:5], off
	global_load_dword v19, v[4:5], off offset:2048
	v_add_co_u32_e32 v4, vcc, s4, v0
	s_and_b64 s[4:5], s[14:15], exec
	s_cselect_b32 s4, 32, 48
	s_add_u32 s4, s34, s4
	s_addc_u32 s5, s35, 0
	s_load_dwordx2 s[4:5], s[4:5], 0x0
	v_addc_co_u32_e32 v5, vcc, 0, v1, vcc
	global_load_dword v16, v[0:1], off
	global_load_dword v17, v[0:1], off offset:2048
	global_load_dword v15, v[2:3], off offset:2048
	global_load_dword v20, v[4:5], off
	global_load_dword v21, v[4:5], off offset:2048
	s_waitcnt lgkmcnt(0)
	v_lshl_add_u64 v[0:1], v[138:139], 2, s[4:5]
	s_and_b64 s[4:5], s[14:15], exec
	s_cselect_b32 s4, 0, 0x1c0
	s_or_b32 s34, s4, s97
	global_load_dword v135, v[0:1], off
	v_add_u32_e32 v0, s34, v189
	v_add_u32_e32 v2, s34, v190
	v_mad_i64_i32 v[0:1], s[4:5], v0, s80, v[140:141]
	v_mad_i64_i32 v[4:5], s[4:5], v2, s80, v[140:141]
	global_load_dwordx4 v[104:107], v[0:1], off
	global_load_dwordx4 v[0:3], v[0:1], off offset:1024
	s_nop 0
	global_load_dwordx4 v[100:103], v[4:5], off
	global_load_dwordx4 v[4:7], v[4:5], off offset:1024
	s_mov_b64 s[4:5], exec
	v_readlane_b32 s36, v254, 37
	v_readlane_b32 s37, v254, 38
	s_and_b64 s[36:37], s[4:5], s[36:37]
	s_xor_b64 s[4:5], s[36:37], s[4:5]
	s_mov_b64 exec, s[36:37]
	s_lshl_b32 s0, s95, 5
	s_or_saveexec_b64 s[4:5], s[4:5]
	v_mov_b32_e32 v8, v147
	v_mov_b32_e32 v9, v147
	v_mov_b32_e32 v10, v147
	v_mov_b32_e32 v11, v147
	v_mov_b64_e32 v[22:23], s[0:1]
	s_xor_b64 exec, exec, s[4:5]
	s_cbranch_execz .LBB0_450
	v_add_u32_e32 v8, s34, v188
	v_ashrrev_i32_e32 v9, 31, v8
	v_readlane_b32 s34, v254, 39
	v_lshlrev_b64 v[8:9], 7, v[8:9]
	v_readlane_b32 s35, v254, 40
	v_lshlrev_b32_e32 v10, 1, v124
	v_mov_b32_e32 v11, v147
	v_lshl_add_u64 v[8:9], s[34:35], 0, v[8:9]
	s_lshl_b32 s34, s95, 6
	s_mov_b32 s35, s1
	v_lshl_add_u64 v[8:9], v[8:9], 0, s[34:35]
	v_lshl_add_u64 v[8:9], v[8:9], 0, v[10:11]
	global_load_dwordx4 v[8:11], v[8:9], off
	s_mov_b32 s37, s1
	s_lshl_b32 s36, s95, 5
	v_mov_b64_e32 v[22:23], s[36:37]

; #define LAS __attribute__((address_space(3)))
; #define MFMA16(a, b, c) __builtin_amdgcn_mfma_f32_16x16x32_bf16((a), (b), (c), 0, 0, 0)
; template <bool PASS2>
; __device__ __forceinline__ void gla_pass(LAS unsigned char* lds, const Params& p, int layer) {
;     ...
;                 for (int m8 = 0; m8 < 8; ++m8) { const f32x4 d = *(LAS f32x4*)(lds + SDEC + (m8 * 16 + 4 * fq) * 4);
; #pragma unroll
;                     for (int kb2 = 0; kb2 < 2; ++kb2) {
;                         const int a0 = SK + (kb2 * 32 + fq * 8 + (fr >> 2)) * 272 + (m8 * 16 + 4 * (fr & 3)) * 2;
;                         const s16x4 lo = __builtin_amdgcn_ds_read_tr16_b64_v4i16((LAS s16x4*)(lds + a0));
;                         const s16x4 hi = __builtin_amdgcn_ds_read_tr16_b64_v4i16((LAS s16x4*)(lds + a0 + 4 * 272));
;                         const bf16x8 A = __builtin_shufflevector(lo, hi, 0, 1, 2, 3, 4, 5, 6, 7);
; #pragma unroll
;                         for (int n = 0; n < 2; ++n) accS[m8][n] = MFMA16(A, vf[n][kb2], accS[m8][n]); }
; #pragma unroll
;                     for (int n = 0; n < 2; ++n) accS[m8][n] = accS[m8][n] * d; }
.LBB0_452:
	v_add_u32_e32 v152, 0x14c00, v206
	v_add_u32_e32 v153, v207, v124
	s_mov_b32 s70, s0
	ds_read_b128 v[108:111], v152
	ds_read_b64_tr_b16 v[112:113], v153 offset:17408
	ds_read_b64_tr_b16 v[114:115], v153 offset:18496
	ds_read_b64_tr_b16 v[166:167], v233 offset:17408
	ds_read_b64_tr_b16 v[168:169], v233 offset:18496
	ds_read_b128 v[170:173], v152 offset:64
	ds_read_b64_tr_b16 v[176:177], v153 offset:17440
	ds_read_b64_tr_b16 v[178:179], v153 offset:18528
	ds_read_b64_tr_b16 v[180:181], v233 offset:17440
	ds_read_b64_tr_b16 v[182:183], v233 offset:18528
	v_add_f32_e32 v163, v163, v174
	v_add_f32_e32 v162, v162, v137
	s_cmp_eq_u32 s68, 8
	s_waitcnt lgkmcnt(5)
	v_mfma_f32_16x16x32_bf16 v[64:67], v[112:115], v[92:95], v[64:67]
	v_mfma_f32_16x16x32_bf16 v[52:55], v[112:115], v[96:99], v[52:55]
	v_mfma_f32_16x16x32_bf16 v[64:67], v[166:169], v[84:87], v[64:67]
	v_mfma_f32_16x16x32_bf16 v[52:55], v[166:169], v[88:91], v[52:55]
	ds_read_b128 v[236:239], v152 offset:128
	ds_read_b64_tr_b16 v[240:241], v153 offset:17472
	ds_read_b64_tr_b16 v[242:243], v153 offset:18560
	ds_read_b64_tr_b16 v[244:245], v233 offset:17472
	ds_read_b64_tr_b16 v[246:247], v233 offset:18560
	s_waitcnt lgkmcnt(5)
	v_mfma_f32_16x16x32_bf16 v[40:43], v[176:179], v[92:95], v[40:43]
	v_mfma_f32_16x16x32_bf16 v[20:23], v[176:179], v[96:99], v[20:23]
	v_mfma_f32_16x16x32_bf16 v[40:43], v[180:183], v[84:87], v[40:43]
	v_mfma_f32_16x16x32_bf16 v[20:23], v[180:183], v[88:91], v[20:23]
	v_pk_mul_f32 v[64:65], v[108:109], v[64:65]
	v_pk_mul_f32 v[66:67], v[110:111], v[66:67]
	v_pk_mul_f32 v[52:53], v[108:109], v[52:53]
	v_pk_mul_f32 v[54:55], v[110:111], v[54:55]
	ds_read_b128 v[108:111], v152 offset:192
	ds_read_b64_tr_b16 v[112:113], v153 offset:17504
	ds_read_b64_tr_b16 v[114:115], v153 offset:18592
	ds_read_b64_tr_b16 v[166:167], v233 offset:17504
	ds_read_b64_tr_b16 v[168:169], v233 offset:18592
	s_waitcnt lgkmcnt(5)
	v_mfma_f32_16x16x32_bf16 v[44:47], v[240:243], v[92:95], v[44:47]
	v_mfma_f32_16x16x32_bf16 v[48:51], v[240:243], v[96:99], v[48:51]
	v_mfma_f32_16x16x32_bf16 v[44:47], v[244:247], v[84:87], v[44:47]
	v_mfma_f32_16x16x32_bf16 v[48:51], v[244:247], v[88:91], v[48:51]
	v_pk_mul_f32 v[40:41], v[170:171], v[40:41]
	v_pk_mul_f32 v[42:43], v[172:173], v[42:43]
	v_pk_mul_f32 v[20:21], v[170:171], v[20:21]
	v_pk_mul_f32 v[22:23], v[172:173], v[22:23]
	ds_read_b128 v[170:173], v152 offset:256
	ds_read_b64_tr_b16 v[176:177], v153 offset:17536
	ds_read_b64_tr_b16 v[178:179], v153 offset:18624
	ds_read_b64_tr_b16 v[180:181], v233 offset:17536
	ds_read_b64_tr_b16 v[182:183], v233 offset:18624
	s_waitcnt lgkmcnt(5)
	v_mfma_f32_16x16x32_bf16 v[68:71], v[112:115], v[92:95], v[68:71]
	v_mfma_f32_16x16x32_bf16 v[72:75], v[112:115], v[96:99], v[72:75]
	v_mfma_f32_16x16x32_bf16 v[68:71], v[166:169], v[84:87], v[68:71]
	v_mfma_f32_16x16x32_bf16 v[72:75], v[166:169], v[88:91], v[72:75]
	v_pk_mul_f32 v[44:45], v[236:237], v[44:45]
	v_pk_mul_f32 v[46:47], v[238:239], v[46:47]
	v_pk_mul_f32 v[48:49], v[236:237], v[48:49]
	v_pk_mul_f32 v[50:51], v[238:239], v[50:51]
	ds_read_b128 v[236:239], v152 offset:320
	ds_read_b64_tr_b16 v[240:241], v153 offset:17568
	ds_read_b64_tr_b16 v[242:243], v153 offset:18656
	ds_read_b64_tr_b16 v[244:245], v233 offset:17568
	ds_read_b64_tr_b16 v[246:247], v233 offset:18656
	s_waitcnt lgkmcnt(5)
	v_mfma_f32_16x16x32_bf16 v[56:59], v[176:179], v[92:95], v[56:59]
	v_mfma_f32_16x16x32_bf16 v[60:63], v[176:179], v[96:99], v[60:63]
	v_mfma_f32_16x16x32_bf16 v[56:59], v[180:183], v[84:87], v[56:59]
	v_mfma_f32_16x16x32_bf16 v[60:63], v[180:183], v[88:91], v[60:63]
	v_pk_mul_f32 v[68:69], v[108:109], v[68:69]
	v_pk_mul_f32 v[70:71], v[110:111], v[70:71]
	v_pk_mul_f32 v[72:73], v[108:109], v[72:73]
	v_pk_mul_f32 v[74:75], v[110:111], v[74:75]
	ds_read_b128 v[108:111], v152 offset:384
	ds_read_b64_tr_b16 v[112:113], v153 offset:17600
	ds_read_b64_tr_b16 v[114:115], v153 offset:18688
	ds_read_b64_tr_b16 v[166:167], v233 offset:17600
	ds_read_b64_tr_b16 v[168:169], v233 offset:18688
	s_waitcnt lgkmcnt(5)
	v_mfma_f32_16x16x32_bf16 v[32:35], v[240:243], v[92:95], v[32:35]
	v_mfma_f32_16x16x32_bf16 v[36:39], v[240:243], v[96:99], v[36:39]
	v_mfma_f32_16x16x32_bf16 v[32:35], v[244:247], v[84:87], v[32:35]
	v_mfma_f32_16x16x32_bf16 v[36:39], v[244:247], v[88:91], v[36:39]
	v_pk_mul_f32 v[56:57], v[170:171], v[56:57]
	v_pk_mul_f32 v[58:59], v[172:173], v[58:59]
	v_pk_mul_f32 v[60:61], v[170:171], v[60:61]
	v_pk_mul_f32 v[62:63], v[172:173], v[62:63]
	ds_read_b128 v[170:173], v152 offset:448
	ds_read_b64_tr_b16 v[176:177], v153 offset:17632
	ds_read_b64_tr_b16 v[178:179], v153 offset:18720
	ds_read_b64_tr_b16 v[180:181], v233 offset:17632
	ds_read_b64_tr_b16 v[182:183], v233 offset:18720
	s_waitcnt lgkmcnt(5)
	v_mfma_f32_16x16x32_bf16 v[24:27], v[112:115], v[92:95], v[24:27]
	v_mfma_f32_16x16x32_bf16 v[28:31], v[112:115], v[96:99], v[28:31]
	v_mfma_f32_16x16x32_bf16 v[24:27], v[166:169], v[84:87], v[24:27]
	v_mfma_f32_16x16x32_bf16 v[28:31], v[166:169], v[88:91], v[28:31]
	v_pk_mul_f32 v[32:33], v[236:237], v[32:33]
	v_pk_mul_f32 v[34:35], v[238:239], v[34:35]
	v_pk_mul_f32 v[36:37], v[236:237], v[36:37]
	v_pk_mul_f32 v[38:39], v[238:239], v[38:39]
	s_waitcnt lgkmcnt(0)
	s_barrier
	v_mfma_f32_16x16x32_bf16 v[76:79], v[176:179], v[92:95], v[76:79]
	v_mfma_f32_16x16x32_bf16 v[80:83], v[176:179], v[96:99], v[80:83]
	v_mfma_f32_16x16x32_bf16 v[76:79], v[180:183], v[84:87], v[76:79]
	v_mfma_f32_16x16x32_bf16 v[80:83], v[180:183], v[88:91], v[80:83]
	v_pk_mul_f32 v[24:25], v[108:109], v[24:25]
	v_pk_mul_f32 v[26:27], v[110:111], v[26:27]
	v_pk_mul_f32 v[28:29], v[108:109], v[28:29]
	v_pk_mul_f32 v[30:31], v[110:111], v[30:31]
	s_nop 7
	v_pk_mul_f32 v[76:77], v[170:171], v[76:77]
	v_pk_mul_f32 v[78:79], v[172:173], v[78:79]
	v_pk_mul_f32 v[80:81], v[170:171], v[80:81]
	v_pk_mul_f32 v[82:83], v[172:173], v[82:83]
	s_cbranch_scc1 .LBB0_515
; #define LAS __attribute__((address_space(3)))
; template <bool PASS2>
; __device__ __forceinline__ void gla_pass(LAS unsigned char* lds, const Params& p, int layer) {
;     ...
;                 const int chunk = dir ? 7 - cc : cc;
;                 const int t0 = b * SEQL + grp * 512 + chunk * 64;
; #pragma unroll
;                 for (int it = 0; it < 2; ++it) { const int pi = tid + 512 * it, row = pi >> 4, seg = pi & 15;
;                     *(LAS u32x4*)(lds + SK + row * 272 + seg * 16) = rk[it];
;                     if (PASS2) rq[it] = *(const u32x4*)(P + (size_t)(t0 + row) * PW + h * 128 + seg * 8); }
; #pragma unroll
;                 for (int it = 0; it < 4; ++it) { const int pi = tid + 512 * it, row = pi >> 5, seg = pi & 31;
;                     rv[it] = *(const u32x4*)(P + (size_t)(t0 + row) * PW + 1024 + h * 256 + seg * 8); }
;                 if (tid < 256) { const int row = tid >> 2, seg = tid & 3; *(LAS u32x4*)(lds + SLR + row * 64 + seg * 16) = rl; }
;                 __syncthreads();
; #pragma unroll 1
;                 for (int m = 0; m < 4; ++m) {
;                     const bf16x8 A = *(LAS bf16x8*)(lds + SLR + (m * 16 + fr) * 64 + fq * 16);
;                     f32x4 xx = (f32x4){0.f, 0.f, 0.f, 0.f};
;                     xx = MFMA16(A, wB1, xx); xx = MFMA16(A, wB2, xx);
; #pragma unroll
;                     for (int jj = 0; jj < 4; ++jj) { const float x = xx[jj] + biasx; const float ls = fminf(x, 0.f) - __logf(1.f + __expf(-fabsf(x)));
;                         *(LAS float*)(lds + SX + ((m * 16 + 4 * fq + jj) * 132 + wid * 16 + fr) * 4) = ls * 0.0625f; }
;                 }
;                 if (PASS2) {
; #pragma unroll
;                     for (int it = 0; it < 2; ++it) { const int pi = tid + 512 * it, row = pi >> 4, seg = pi & 15; *(LAS u32x4*)(lds + SQ + row * 272 + seg * 16) = rq[it]; } }
;                 __syncthreads();
;                 float c0[8], c1[8];
; #pragma unroll
;                 for (int e = 0; e < 8; ++e) { const f32x2 t2 = *(LAS f32x2*)(lds + SX + ((wid * 8 + e) * 132 + dk0) * 4); c0[e] = t2.x; c1[e] = t2.y; }
;                 if (dir == 0) {
; #pragma unroll
;                     for (int e = 1; e < 8; ++e) { c0[e] += c0[e - 1]; c1[e] += c1[e - 1]; }
;                 } else {
; #pragma unroll
;                     for (int e = 6; e >= 0; --e) { c0[e] += c0[e + 1]; c1[e] += c1[e + 1]; }
.LBB0_453:
	s_sub_i32 s66, 7, s68
	s_and_b64 s[4:5], s[14:15], exec
	s_cselect_b32 s4, s68, s66
	s_lshl_b32 s69, s4, 6
	s_add_i32 s69, s69, s97
	v_add_u32_e32 v84, s69, v189
	v_add_u32_e32 v86, s69, v190
	v_mad_i64_i32 v[84:85], s[4:5], v84, s80, v[140:141]
	v_mad_i64_i32 v[86:87], s[4:5], v86, s80, v[140:141]
	v_add_u32_e32 v84, s69, v193
	v_add_u32_e32 v86, s69, v194
	v_add_u32_e32 v92, s69, v195
	v_add_u32_e32 v94, s69, v196
	v_mad_i64_i32 v[84:85], s[4:5], v84, s80, v[160:161]
	v_mad_i64_i32 v[88:89], s[4:5], v86, s80, v[160:161]
	v_mad_i64_i32 v[92:93], s[4:5], v92, s80, v[160:161]
	v_mad_i64_i32 v[96:97], s[4:5], v94, s80, v[160:161]
	global_load_dwordx4 v[84:87], v[84:85], off offset:2048
	s_nop 0
	global_load_dwordx4 v[88:91], v[88:89], off offset:2048
	s_nop 0
	global_load_dwordx4 v[92:95], v[92:93], off offset:2048
	s_nop 0
	global_load_dwordx4 v[96:99], v[96:97], off offset:2048
	v_add_u32_e32 v108, v184, v191
	s_waitcnt vmcnt(6)
	ds_write_b128 v108, v[0:3] offset:17408
	v_add_u32_e32 v108, v184, v192
	s_waitcnt vmcnt(6)
	ds_write_b128 v108, v[4:7] offset:17408
	s_and_saveexec_b64 s[4:5], s[12:13]
	ds_write_b128 v211, v[8:11]
	s_or_b64 exec, exec, s[4:5]
	s_sub_i32 s66, 6, s68
	s_add_i32 s4, s68, 1
	s_and_b64 vcc, s[14:15], exec
	s_cselect_b32 s4, s4, s66
	s_lshl_b32 s66, s4, 6
	s_add_i32 s66, s66, s97
	v_add_u32_e32 v0, s66, v189
	v_add_u32_e32 v2, s66, v190
	v_mad_i64_i32 v[0:1], s[4:5], v0, s80, v[140:141]
	v_mad_i64_i32 v[4:5], s[4:5], v2, s80, v[140:141]
	global_load_dwordx4 v[0:3], v[0:1], off offset:1024
	s_nop 0
	global_load_dwordx4 v[4:7], v[4:5], off offset:1024
	s_and_saveexec_b64 s[4:5], s[12:13]
	s_cbranch_execz .Lgla_t3_skip
	v_add_u32_e32 v8, s66, v188
	v_ashrrev_i32_e32 v9, 31, v8
	v_lshlrev_b64 v[8:9], 7, v[8:9]
	v_lshl_add_u64 v[8:9], v[164:165], 0, v[8:9]
	global_load_dwordx4 v[8:11], v[8:9], off
.Lgla_t3_skip:
	s_or_b64 exec, exec, s[4:5]
	s_mov_b32 s4, 4
	v_mov_b32_e32 v108, v210
	v_mov_b32_e32 v109, v209
	v_mov_b32_e32 v110, v208
	s_waitcnt lgkmcnt(0)
	s_barrier
.LBB0_456:
	v_add_u32_e32 v111, 0, v110
	ds_read_b128 v[112:115], v111
	s_add_i32 s4, s4, -1
	v_add_u32_e32 v110, 0x400, v110
	s_cmp_lg_u32 s4, 0
	s_waitcnt lgkmcnt(0)
	v_mfma_f32_16x16x32_bf16 v[166:169], v[112:115], v[12:15], 0
	v_mfma_f32_16x16x32_bf16 v[112:115], v[112:115], v[16:19], v[166:169]
	s_nop 7
	v_add_f32_e32 v111, v135, v112
	v_min_f32_e32 v112, 0, v111
	v_mul_f32_e64 v111, |v111|, s79
	v_exp_f32_e32 v111, v111
	s_nop 0
	v_add_f32_e32 v111, 1.0, v111
	v_cmp_gt_f32_e32 vcc, s33, v111
	s_nop 1
	v_cndmask_b32_e64 v137, 0, 32, vcc
	v_ldexp_f32 v111, v111, v137
	v_log_f32_e32 v111, v111
	s_nop 0
	v_mul_f32_e32 v137, 0x3f317217, v111
	v_fma_f32 v137, v111, s81, -v137
	v_fmac_f32_e32 v137, 0x3377d1cf, v111
	v_fmac_f32_e32 v137, 0x3f317217, v111
	v_cmp_lt_f32_e64 s[66:67], |v111|, s90
	s_nop 1
	v_cndmask_b32_e64 v111, v111, v137, s[66:67]
	v_cndmask_b32_e32 v137, 0, v225, vcc
	v_sub_f32_e32 v111, v111, v137
	v_sub_f32_e32 v111, v112, v111
	v_mul_f32_e32 v111, 0x3d800000, v111
	v_add_u32_e32 v112, 0, v109
	ds_write_b32 v112, v111
	v_add_f32_e32 v111, v135, v113
	v_min_f32_e32 v112, 0, v111
	v_mul_f32_e64 v111, |v111|, s79
	v_exp_f32_e32 v111, v111
	v_add_u32_e32 v109, 0x2100, v109
	v_add_f32_e32 v111, 1.0, v111
	v_cmp_gt_f32_e32 vcc, s33, v111
	s_nop 1
	v_cndmask_b32_e64 v113, 0, 32, vcc
	v_ldexp_f32 v111, v111, v113
	v_log_f32_e32 v111, v111
	s_nop 0
	v_mul_f32_e32 v113, 0x3f317217, v111
	v_fma_f32 v113, v111, s81, -v113
	v_fmac_f32_e32 v113, 0x3377d1cf, v111
	v_fmac_f32_e32 v113, 0x3f317217, v111
	v_cmp_lt_f32_e64 s[66:67], |v111|, s90
	s_nop 1
	v_cndmask_b32_e64 v111, v111, v113, s[66:67]
	v_cndmask_b32_e32 v113, 0, v225, vcc
	v_sub_f32_e32 v111, v111, v113
	v_sub_f32_e32 v111, v112, v111
	v_add_u32_e32 v112, 0, v108
	v_mul_f32_e32 v111, 0x3d800000, v111
	v_add_u32_e32 v113, 0x15010, v112
	ds_write_b32 v113, v111
	v_add_f32_e32 v111, v135, v114
	v_min_f32_e32 v113, 0, v111
	v_mul_f32_e64 v111, |v111|, s79
	v_exp_f32_e32 v111, v111
	v_add_u32_e32 v108, 0x2100, v108
	v_add_f32_e32 v111, 1.0, v111
	v_cmp_gt_f32_e32 vcc, s33, v111
	s_nop 1
	v_cndmask_b32_e64 v114, 0, 32, vcc
	v_ldexp_f32 v111, v111, v114
	v_log_f32_e32 v111, v111
	s_nop 0
	v_mul_f32_e32 v114, 0x3f317217, v111
	v_fma_f32 v114, v111, s81, -v114
	v_fmac_f32_e32 v114, 0x3377d1cf, v111
	v_fmac_f32_e32 v114, 0x3f317217, v111
	v_cmp_lt_f32_e64 s[66:67], |v111|, s90
	s_nop 1
	v_cndmask_b32_e64 v111, v111, v114, s[66:67]
	v_cndmask_b32_e32 v114, 0, v225, vcc
	v_sub_f32_e32 v111, v111, v114
	v_sub_f32_e32 v111, v113, v111
	v_mul_f32_e32 v111, 0x3d800000, v111
	v_add_u32_e32 v113, 0x15220, v112
	ds_write_b32 v113, v111
	v_add_f32_e32 v111, v135, v115
	v_min_f32_e32 v113, 0, v111
	v_mul_f32_e64 v111, |v111|, s79
	v_exp_f32_e32 v111, v111
	v_add_u32_e32 v112, 0x15430, v112
	v_add_f32_e32 v111, 1.0, v111
	v_cmp_gt_f32_e32 vcc, s33, v111
	s_nop 1
	v_cndmask_b32_e64 v114, 0, 32, vcc
	v_ldexp_f32 v111, v111, v114
	v_log_f32_e32 v111, v111
	s_nop 0
	v_mul_f32_e32 v114, 0x3f317217, v111
	v_fma_f32 v114, v111, s81, -v114
	v_fmac_f32_e32 v114, 0x3377d1cf, v111
	v_fmac_f32_e32 v114, 0x3f317217, v111
	v_cmp_lt_f32_e64 s[66:67], |v111|, s90
	s_nop 1
	v_cndmask_b32_e64 v111, v111, v114, s[66:67]
	v_cndmask_b32_e32 v114, 0, v225, vcc
	v_sub_f32_e32 v111, v111, v114
	v_sub_f32_e32 v111, v113, v111
	v_mul_f32_e32 v111, 0x3d800000, v111
	ds_write_b32 v112, v111
	s_cbranch_scc1 .LBB0_456
	v_add_u32_e32 v108, v185, v191
	s_waitcnt vmcnt(7)
	ds_write_b128 v108, v[104:107]
	v_add_u32_e32 v104, v185, v192
	s_waitcnt vmcnt(6)
	ds_write_b128 v104, v[100:103]
	s_waitcnt lgkmcnt(0)
	s_barrier
	ds_read_b64 v[100:101], v197
	ds_read_b64 v[102:103], v198
	ds_read_b64 v[104:105], v199
	ds_read_b64 v[106:107], v200
	ds_read_b64 v[108:109], v201
	ds_read_b64 v[110:111], v202
	ds_read_b64 v[112:113], v203
	ds_read_b64 v[166:167], v204
	v_cndmask_b32_e64 v114, 0, 1, s[86:87]
	v_cmp_ne_u32_e64 s[66:67], 1, v114
	s_andn2_b64 vcc, exec, s[86:87]
	s_mov_b64 s[4:5], -1
	s_cbranch_vccnz .LBB0_459
	s_waitcnt lgkmcnt(0)
	v_pk_add_f32 v[168:169], v[112:113], v[166:167]
	s_mov_b64 s[4:5], 0
	v_pk_add_f32 v[170:171], v[110:111], v[168:169]
	s_nop 0
	v_pk_add_f32 v[172:173], v[108:109], v[170:171]
	s_nop 0
	v_pk_add_f32 v[174:175], v[106:107], v[172:173]
	s_nop 0
	v_pk_add_f32 v[176:177], v[104:105], v[174:175]
	s_nop 0
	v_pk_add_f32 v[178:179], v[102:103], v[176:177]
	s_nop 0
	v_pk_add_f32 v[180:181], v[100:101], v[178:179]

; #define LAS __attribute__((address_space(3)))
; __device__ __forceinline__ unsigned cvt_pk_bf16(float lo, float hi) { const f32x2 v = {lo, hi}; const bf16x2_t b = __builtin_convertvector(v, bf16x2_t); return __builtin_bit_cast(unsigned, b); }
; #define MFMA16(a, b, c) __builtin_amdgcn_mfma_f32_16x16x32_bf16((a), (b), (c), 0, 0, 0)
; template <bool PASS2>
; __device__ __forceinline__ void gla_pass(LAS unsigned char* lds, const Params& p, int layer) {
;     ...
;                 for (int it = 0; it < 4; ++it) { const int pi = tid + 512 * it, row = pi >> 5, seg = pi & 31;
;                     *(LAS u32x4*)(lds + SV + row * 528 + seg * 16) = rv[it]; }
;                 __syncthreads();
;                 if (PASS2) {
;                     f32x4 accP[2];
; #pragma unroll
;                     for (int s = 0; s < 2; ++s) { const int tt = wid * 2 + s, ib = tt >> 2, jb = tt & 3; f32x4 a = (f32x4){0.f, 0.f, 0.f, 0.f};
; #pragma unroll
;                         for (int kb = 0; kb < 4; ++kb) { const bf16x8 A = *(LAS bf16x8*)(lds + SK + (jb * 16 + fr) * 272 + (kb * 32 + fq * 8) * 2);
;                             const bf16x8 B = *(LAS bf16x8*)(lds + SQ + (ib * 16 + fr) * 272 + (kb * 32 + fq * 8) * 2); a = MFMA16(A, B, a); }
;                         accP[s] = a; }
; #pragma unroll
;                     for (int s = 0; s < 2; ++s) { const int tt = wid * 2 + s, ib = tt >> 2, jb = tt & 3; const int i = ib * 16 + fr, jbase = jb * 16 + 4 * fq; float v[4];
; #pragma unroll
;                         for (int jj = 0; jj < 4; ++jj) { const int j = jbase + jj; const bool keep = dir == 0 ? (j <= i) : (j > i); v[jj] = keep ? accP[s][jj] : 0.f; }
;                         *(LAS u32x2*)(lds + SP + i * 144 + jbase * 2) = (u32x2){cvt_pk_bf16(v[0], v[1]), cvt_pk_bf16(v[2], v[3])}; }
; #pragma unroll
;                     for (int m8 = 0; m8 < 8; ++m8)
; #pragma unroll
;                         for (int n = 0; n < 2; ++n) { const f32x4 sv = accS[m8][n];
;                             *(LAS u32x2*)(lds + SST + (wid * 32 + n * 16 + fr) * 272 + (m8 * 16 + 4 * fq) * 2) = (u32x2){cvt_pk_bf16(sv[0], sv[1]), cvt_pk_bf16(sv[2], sv[3])}; }
;                     __syncthreads();
;     ...
;                         for (int m = 0; m < 4; ++m) { bf16_t* dst = O + (size_t)(t0 + m * 16 + fr) * 1024 + h * 256 + wid * 32 + n * 16 + 4 * fq; f32x4 v = accO[m];
.LBB0_495:
	s_waitcnt vmcnt(13)
	ds_write_b128 v212, v[84:87] offset:35840
	s_waitcnt vmcnt(12)
	ds_write_b128 v213, v[88:91] offset:35840
	s_waitcnt vmcnt(11)
	ds_write_b128 v214, v[92:95] offset:35840
	s_waitcnt vmcnt(10)
	ds_write_b128 v215, v[96:99] offset:35840
	v_or_b32_e32 v250, s69, v116
	v_mbcnt_lo_u32_b32 v253, -1, 0
	v_ashrrev_i32_e32 v251, 31, v250
	v_mbcnt_hi_u32_b32 v253, -1, v253
	v_lshlrev_b64 v[250:251], 11, v[250:251]
	v_and_b32_e32 v252, 15, v253
	v_lshl_add_u64 v[250:251], v[158:159], 0, v[250:251]
	v_lshrrev_b32_e32 v253, 4, v253
	v_lshlrev_b32_e32 v252, 11, v252
	v_readfirstlane_b32 s4, v250
	v_readfirstlane_b32 s5, v251
	v_lshl_or_b32 v153, v253, 3, v252
	s_and_b64 vcc, exec, s[66:67]
	s_cbranch_vccnz .Lgla_opf_skip
	s_nop 3
	global_load_dwordx2 v[244:245], v153, s[4:5]
	s_add_u32 s4, s4, 0x8000
	s_addc_u32 s5, s5, 0
	global_load_dwordx2 v[246:247], v153, s[4:5]
	s_add_u32 s4, s4, 0x8000
	s_addc_u32 s5, s5, 0
	global_load_dwordx2 v[250:251], v153, s[4:5]
	s_add_u32 s4, s4, 0x8000
	s_addc_u32 s5, s5, 0
	global_load_dwordx2 v[252:253], v153, s[4:5]
	s_sub_u32 s4, s4, 0x18000
	s_subb_u32 s5, s5, 0
.Lgla_opf_skip:
	s_waitcnt lgkmcnt(0)
	s_barrier
	ds_read_b128 v[84:87], v216 offset:17408
	ds_read_b128 v[88:91], v217
	ds_read_b128 v[92:95], v216 offset:17472
	s_waitcnt lgkmcnt(1)
	v_mfma_f32_16x16x32_bf16 v[84:87], v[84:87], v[88:91], 0
	ds_read_b128 v[96:99], v217 offset:64
	ds_read_b128 v[100:103], v216 offset:17536
	v_add_u32_e32 v152, v205, v124
	s_and_b64 vcc, exec, s[66:67]
	s_waitcnt lgkmcnt(1)
	v_mfma_f32_16x16x32_bf16 v[84:87], v[92:95], v[96:99], v[84:87]
	ds_read_b128 v[92:95], v217 offset:128
	ds_read_b128 v[104:107], v218 offset:17408
	s_waitcnt lgkmcnt(1)
	v_mfma_f32_16x16x32_bf16 v[84:87], v[100:103], v[92:95], v[84:87]
	ds_read_b128 v[100:103], v216 offset:17600
	ds_read_b128 v[108:111], v217 offset:192
	s_waitcnt lgkmcnt(2)
	v_mfma_f32_16x16x32_bf16 v[88:91], v[104:107], v[88:91], 0
	ds_read_b128 v[104:107], v218 offset:17472
	s_waitcnt lgkmcnt(1)
	v_mfma_f32_16x16x32_bf16 v[84:87], v[100:103], v[108:111], v[84:87]
	ds_read_b128 v[100:103], v218 offset:17536
	s_waitcnt lgkmcnt(1)
	v_mfma_f32_16x16x32_bf16 v[88:91], v[104:107], v[96:99], v[88:91]
	ds_read_b128 v[96:99], v218 offset:17600
	s_nop 3
	v_cndmask_b32_e64 v104, 0, v84, s[50:51]
	s_waitcnt lgkmcnt(1)
	v_mfma_f32_16x16x32_bf16 v[88:91], v[100:103], v[92:95], v[88:91]
	v_cndmask_b32_e64 v92, 0, v85, s[52:53]
	v_cndmask_b32_e64 v93, 0, v86, s[54:55]
	v_cndmask_b32_e64 v94, 0, v87, s[56:57]
	s_waitcnt lgkmcnt(0)
	v_mfma_f32_16x16x32_bf16 v[84:87], v[96:99], v[108:111], v[88:91]
	s_nop 2
	v_cvt_pk_bf16_f32 v88, v104, v92
	s_nop 3
	v_cndmask_b32_e64 v84, 0, v84, s[58:59]
	v_cndmask_b32_e64 v85, 0, v85, s[60:61]
	v_cndmask_b32_e64 v86, 0, v86, s[62:63]
	v_cndmask_b32_e64 v87, 0, v87, s[64:65]
	v_cvt_pk_bf16_f32 v89, v93, v94
	v_cvt_pk_bf16_f32 v84, v84, v85
	v_cvt_pk_bf16_f32 v85, v86, v87
	ds_write_b64 v219, v[88:89]
	ds_write_b64 v227, v[84:85]
	v_cvt_pk_bf16_f32 v84, v64, v65
	v_cvt_pk_bf16_f32 v85, v66, v67
	v_cvt_pk_bf16_f32 v88, v40, v41
	v_cvt_pk_bf16_f32 v89, v42, v43
	v_cvt_pk_bf16_f32 v86, v52, v53
	v_cvt_pk_bf16_f32 v87, v54, v55
	ds_write2_b64 v228, v[84:85], v[88:89] offset1:4
	v_cvt_pk_bf16_f32 v84, v20, v21
	v_cvt_pk_bf16_f32 v85, v22, v23
	v_add_u32_e32 v90, 0x1000, v228
	ds_write2_b64 v90, v[86:87], v[84:85] offset0:32 offset1:36
	v_cvt_pk_bf16_f32 v84, v44, v45
	v_cvt_pk_bf16_f32 v85, v46, v47
	v_cvt_pk_bf16_f32 v88, v68, v69
	v_cvt_pk_bf16_f32 v89, v70, v71
	v_cvt_pk_bf16_f32 v86, v48, v49
	v_cvt_pk_bf16_f32 v87, v50, v51
	ds_write2_b64 v228, v[84:85], v[88:89] offset0:8 offset1:12
	v_cvt_pk_bf16_f32 v84, v72, v73
	v_cvt_pk_bf16_f32 v85, v74, v75
	ds_write2_b64 v90, v[86:87], v[84:85] offset0:40 offset1:44
	v_cvt_pk_bf16_f32 v84, v56, v57
	v_cvt_pk_bf16_f32 v85, v58, v59
	v_cvt_pk_bf16_f32 v88, v32, v33
	v_cvt_pk_bf16_f32 v89, v34, v35
	v_cvt_pk_bf16_f32 v86, v60, v61
	v_cvt_pk_bf16_f32 v87, v62, v63
	ds_write2_b64 v228, v[84:85], v[88:89] offset0:16 offset1:20
	v_cvt_pk_bf16_f32 v84, v36, v37
	v_cvt_pk_bf16_f32 v85, v38, v39
	ds_write2_b64 v90, v[86:87], v[84:85] offset0:48 offset1:52
	v_cvt_pk_bf16_f32 v84, v24, v25
	v_cvt_pk_bf16_f32 v85, v26, v27
	v_cvt_pk_bf16_f32 v88, v76, v77
	v_cvt_pk_bf16_f32 v89, v78, v79
	v_cvt_pk_bf16_f32 v86, v28, v29
	v_cvt_pk_bf16_f32 v87, v30, v31
	ds_write2_b64 v228, v[84:85], v[88:89] offset0:24 offset1:28
	v_cvt_pk_bf16_f32 v84, v80, v81
	v_cvt_pk_bf16_f32 v85, v82, v83
	ds_write2_b64 v90, v[86:87], v[84:85] offset0:56 offset1:60
	s_waitcnt lgkmcnt(0)
	s_barrier
; #define LAS __attribute__((address_space(3)))
; __device__ __forceinline__ unsigned cvt_pk_bf16(float lo, float hi) { const f32x2 v = {lo, hi}; const bf16x2_t b = __builtin_convertvector(v, bf16x2_t); return __builtin_bit_cast(unsigned, b); }
; template <bool PASS2>
; __device__ __forceinline__ void gla_pass(LAS unsigned char* lds, const Params& p, int layer) {
;     ...
;                 bf16x8 vf[2][2];
; #pragma unroll
;                 for (int n = 0; n < 2; ++n)
; #pragma unroll
;                     for (int kb2 = 0; kb2 < 2; ++kb2) {
;                         const int a0 = SV + (kb2 * 32 + fq * 8 + (fr >> 2)) * 528 + (wid * 32 + n * 16 + 4 * (fr & 3)) * 2;
;                         const s16x4 lo = __builtin_amdgcn_ds_read_tr16_b64_v4i16((LAS s16x4*)(lds + a0));
;                         const s16x4 hi = __builtin_amdgcn_ds_read_tr16_b64_v4i16((LAS s16x4*)(lds + a0 + 4 * 528));
;                         vf[n][kb2] = __builtin_shufflevector(lo, hi, 0, 1, 2, 3, 4, 5, 6, 7); }
;                 if (PASS2) {
; #pragma unroll
;                     for (int n = 0; n < 2; ++n) {
;                         f32x4 accO[4];
; #pragma unroll
;                         for (int m = 0; m < 4; ++m) accO[m] = (f32x4){0.f, 0.f, 0.f, 0.f};
; #pragma unroll
;                         for (int kb = 0; kb < 4; ++kb) { const bf16x8 A = *(LAS bf16x8*)(lds + SST + (wid * 32 + n * 16 + fr) * 272 + (kb * 32 + fq * 8) * 2);
; #pragma unroll
;                             for (int m = 0; m < 4; ++m) { const bf16x8 B = *(LAS bf16x8*)(lds + SQ + (m * 16 + fr) * 272 + (kb * 32 + fq * 8) * 2); accO[m] = MFMA16(A, B, accO[m]); } }
; #pragma unroll
;                         for (int kb2 = 0; kb2 < 2; ++kb2)
; #pragma unroll
;                             for (int m = 0; m < 4; ++m) { const bf16x8 B = *(LAS bf16x8*)(lds + SP + (m * 16 + fr) * 144 + (kb2 * 32 + fq * 8) * 2); accO[m] = MFMA16(vf[n][kb2], B, accO[m]); }
; #pragma unroll
;                         for (int m = 0; m < 4; ++m) { bf16_t* dst = O + (size_t)(t0 + m * 16 + fr) * 1024 + h * 256 + wid * 32 + n * 16 + 4 * fq; f32x4 v = accO[m];
;                             if (dir) { const u32x2 old = *(const u32x2*)dst; v[0] += bflo(old.x); v[1] += bfhi(old.x); v[2] += bflo(old.y); v[3] += bfhi(old.y); }
;                             *(u32x2*)dst = (u32x2){cvt_pk_bf16(v[0], v[1]), cvt_pk_bf16(v[2], v[3])}; }
	ds_read_b64_tr_b16 v[92:93], v152 offset:35840
	ds_read_b64_tr_b16 v[94:95], v152 offset:37952
	ds_read_b64_tr_b16 v[84:85], v229 offset:35840
	ds_read_b64_tr_b16 v[86:87], v229 offset:37952
	ds_read_b64_tr_b16 v[96:97], v152 offset:35872
	ds_read_b64_tr_b16 v[98:99], v152 offset:37984
	ds_read_b64_tr_b16 v[88:89], v229 offset:35872
	ds_read_b64_tr_b16 v[90:91], v229 offset:37984
	ds_read_b128 v[166:169], v230
	ds_read_b128 v[170:173], v234
	ds_read_b128 v[176:179], v234 offset:4352
	ds_read_b128 v[180:183], v234 offset:8704
	ds_read_b128 v[236:239], v234 offset:13056
	ds_read_b128 v[240:243], v230 offset:64
	s_waitcnt lgkmcnt(4)
	v_mfma_f32_16x16x32_bf16 v[100:103], v[166:169], v[170:173], 0
	ds_read_b128 v[170:173], v234 offset:64
	s_waitcnt lgkmcnt(4)
	v_mfma_f32_16x16x32_bf16 v[104:107], v[166:169], v[176:179], 0
	ds_read_b128 v[176:179], v234 offset:4416
	s_waitcnt lgkmcnt(4)
	v_mfma_f32_16x16x32_bf16 v[108:111], v[166:169], v[180:183], 0
	ds_read_b128 v[180:183], v234 offset:8768
	s_waitcnt lgkmcnt(4)
	v_mfma_f32_16x16x32_bf16 v[112:115], v[166:169], v[236:239], 0
	ds_read_b128 v[166:169], v234 offset:13120
	ds_read_b128 v[236:239], v230 offset:128
	s_waitcnt lgkmcnt(4)
	v_mfma_f32_16x16x32_bf16 v[100:103], v[240:243], v[170:173], v[100:103]
	ds_read_b128 v[170:173], v234 offset:128
	s_waitcnt lgkmcnt(4)
	v_mfma_f32_16x16x32_bf16 v[104:107], v[240:243], v[176:179], v[104:107]
	ds_read_b128 v[176:179], v234 offset:4480
	s_waitcnt lgkmcnt(4)
	v_mfma_f32_16x16x32_bf16 v[108:111], v[240:243], v[180:183], v[108:111]
	ds_read_b128 v[180:183], v234 offset:8832
	s_waitcnt lgkmcnt(4)
	v_mfma_f32_16x16x32_bf16 v[112:115], v[240:243], v[166:169], v[112:115]
	ds_read_b128 v[240:243], v234 offset:13184
	ds_read_b128 v[166:169], v230 offset:192
	s_waitcnt lgkmcnt(4)
	v_mfma_f32_16x16x32_bf16 v[100:103], v[236:239], v[170:173], v[100:103]
	ds_read_b128 v[170:173], v234 offset:192
	s_waitcnt lgkmcnt(4)
	v_mfma_f32_16x16x32_bf16 v[104:107], v[236:239], v[176:179], v[104:107]
	ds_read_b128 v[176:179], v234 offset:4544
	s_waitcnt lgkmcnt(4)
	v_mfma_f32_16x16x32_bf16 v[108:111], v[236:239], v[180:183], v[108:111]
	ds_read_b128 v[180:183], v234 offset:8896
	s_waitcnt lgkmcnt(4)
	v_mfma_f32_16x16x32_bf16 v[112:115], v[236:239], v[240:243], v[112:115]
	ds_read_b128 v[236:239], v234 offset:13248
	ds_read_b128 v[240:243], v235
	s_waitcnt lgkmcnt(4)
	v_mfma_f32_16x16x32_bf16 v[100:103], v[166:169], v[170:173], v[100:103]
	ds_read_b128 v[170:173], v235 offset:2304
	s_waitcnt lgkmcnt(4)
	v_mfma_f32_16x16x32_bf16 v[104:107], v[166:169], v[176:179], v[104:107]
	ds_read_b128 v[176:179], v235 offset:4608
	s_waitcnt lgkmcnt(4)
	v_mfma_f32_16x16x32_bf16 v[108:111], v[166:169], v[180:183], v[108:111]
	ds_read_b128 v[180:183], v235 offset:6912
	s_waitcnt lgkmcnt(4)
	v_mfma_f32_16x16x32_bf16 v[112:115], v[166:169], v[236:239], v[112:115]
	ds_read_b128 v[166:169], v235 offset:64
	ds_read_b128 v[236:239], v235 offset:2368
	s_waitcnt lgkmcnt(5)
	v_mfma_f32_16x16x32_bf16 v[100:103], v[92:95], v[240:243], v[100:103]
	ds_read_b128 v[240:243], v235 offset:4672
	s_waitcnt lgkmcnt(5)
	v_mfma_f32_16x16x32_bf16 v[104:107], v[92:95], v[170:173], v[104:107]
	ds_read_b128 v[170:173], v235 offset:6976
	s_waitcnt lgkmcnt(5)
	v_mfma_f32_16x16x32_bf16 v[108:111], v[92:95], v[176:179], v[108:111]
	s_waitcnt lgkmcnt(4)
	v_mfma_f32_16x16x32_bf16 v[112:115], v[92:95], v[180:183], v[112:115]
	s_waitcnt lgkmcnt(3)
	v_mfma_f32_16x16x32_bf16 v[100:103], v[84:87], v[166:169], v[100:103]
	s_waitcnt lgkmcnt(2)
	v_mfma_f32_16x16x32_bf16 v[104:107], v[84:87], v[236:239], v[104:107]
	s_waitcnt lgkmcnt(1)
	v_mfma_f32_16x16x32_bf16 v[108:111], v[84:87], v[240:243], v[108:111]
	s_waitcnt lgkmcnt(0)
	v_mfma_f32_16x16x32_bf16 v[112:115], v[84:87], v[170:173], v[112:115]
	s_nop 7
	s_and_b64 vcc, exec, s[66:67]
	s_cbranch_vccnz .Lgla_s4_skip0
	s_waitcnt vmcnt(0)
	v_lshlrev_b32_e32 v166, 16, v244
	v_and_b32_e32 v167, 0xffff0000, v244
	v_lshlrev_b32_e32 v168, 16, v245
	v_and_b32_e32 v169, 0xffff0000, v245
	v_pk_add_f32 v[100:101], v[100:101], v[166:167]
	v_pk_add_f32 v[102:103], v[102:103], v[168:169]
	v_lshlrev_b32_e32 v166, 16, v246
	v_and_b32_e32 v167, 0xffff0000, v246
	v_lshlrev_b32_e32 v168, 16, v247
	v_and_b32_e32 v169, 0xffff0000, v247
	v_pk_add_f32 v[104:105], v[104:105], v[166:167]
	v_pk_add_f32 v[106:107], v[106:107], v[168:169]
	v_lshlrev_b32_e32 v166, 16, v250
	v_and_b32_e32 v167, 0xffff0000, v250
	v_lshlrev_b32_e32 v168, 16, v251
	v_and_b32_e32 v169, 0xffff0000, v251
	v_pk_add_f32 v[108:109], v[108:109], v[166:167]
	v_pk_add_f32 v[110:111], v[110:111], v[168:169]
	v_lshlrev_b32_e32 v166, 16, v252
	v_and_b32_e32 v167, 0xffff0000, v252
	v_lshlrev_b32_e32 v168, 16, v253
	v_and_b32_e32 v169, 0xffff0000, v253
	v_pk_add_f32 v[112:113], v[112:113], v[166:167]
	v_pk_add_f32 v[114:115], v[114:115], v[168:169]
	global_load_dwordx2 v[244:245], v153, s[4:5] offset:32
	s_add_u32 s4, s4, 0x8000
	s_addc_u32 s5, s5, 0
	global_load_dwordx2 v[246:247], v153, s[4:5] offset:32
	s_add_u32 s4, s4, 0x8000
	s_addc_u32 s5, s5, 0
	global_load_dwordx2 v[250:251], v153, s[4:5] offset:32
	s_add_u32 s4, s4, 0x8000
	s_addc_u32 s5, s5, 0
	global_load_dwordx2 v[252:253], v153, s[4:5] offset:32
	s_sub_u32 s4, s4, 0x18000
	s_subb_u32 s5, s5, 0
; #define LAS __attribute__((address_space(3)))
; __device__ __forceinline__ unsigned cvt_pk_bf16(float lo, float hi) { const f32x2 v = {lo, hi}; const bf16x2_t b = __builtin_convertvector(v, bf16x2_t); return __builtin_bit_cast(unsigned, b); }
; __device__ __forceinline__ float bflo(unsigned w) { return __uint_as_float(w << 16); }
; __device__ __forceinline__ float bfhi(unsigned w) { return __uint_as_float(w & 0xffff0000u); }
; #define MFMA16(a, b, c) __builtin_amdgcn_mfma_f32_16x16x32_bf16((a), (b), (c), 0, 0, 0)
; template <bool PASS2>
; __device__ __forceinline__ void gla_pass(LAS unsigned char* lds, const Params& p, int layer) {
;     ...
;                         for (int kb = 0; kb < 4; ++kb) { const bf16x8 A = *(LAS bf16x8*)(lds + SST + (wid * 32 + n * 16 + fr) * 272 + (kb * 32 + fq * 8) * 2);
; #pragma unroll
;                             for (int m = 0; m < 4; ++m) { const bf16x8 B = *(LAS bf16x8*)(lds + SQ + (m * 16 + fr) * 272 + (kb * 32 + fq * 8) * 2); accO[m] = MFMA16(A, B, accO[m]); } }
; #pragma unroll
;                         for (int kb2 = 0; kb2 < 2; ++kb2)
; #pragma unroll
;                             for (int m = 0; m < 4; ++m) { const bf16x8 B = *(LAS bf16x8*)(lds + SP + (m * 16 + fr) * 144 + (kb2 * 32 + fq * 8) * 2); accO[m] = MFMA16(vf[n][kb2], B, accO[m]); }
; #pragma unroll
;                         for (int m = 0; m < 4; ++m) { bf16_t* dst = O + (size_t)(t0 + m * 16 + fr) * 1024 + h * 256 + wid * 32 + n * 16 + 4 * fq; f32x4 v = accO[m];
;                             if (dir) { const u32x2 old = *(const u32x2*)dst; v[0] += bflo(old.x); v[1] += bfhi(old.x); v[2] += bflo(old.y); v[3] += bfhi(old.y); }
;                             *(u32x2*)dst = (u32x2){cvt_pk_bf16(v[0], v[1]), cvt_pk_bf16(v[2], v[3])}; }
;                         asm volatile("" ::: "memory");
;                     }
;                 }
;                 if (cc < 7) GLA_ISSUE(cc + 1);
.Lgla_s4_skip0:
	v_cvt_pk_bf16_f32 v100, v100, v101
	v_cvt_pk_bf16_f32 v101, v102, v103
	global_store_dwordx2 v153, v[100:101], s[4:5]
	s_add_u32 s4, s4, 0x8000
	s_addc_u32 s5, s5, 0
	v_cvt_pk_bf16_f32 v104, v104, v105
	v_cvt_pk_bf16_f32 v105, v106, v107
	global_store_dwordx2 v153, v[104:105], s[4:5]
	s_add_u32 s4, s4, 0x8000
	s_addc_u32 s5, s5, 0
	v_cvt_pk_bf16_f32 v108, v108, v109
	v_cvt_pk_bf16_f32 v109, v110, v111
	global_store_dwordx2 v153, v[108:109], s[4:5]
	s_add_u32 s4, s4, 0x8000
	s_addc_u32 s5, s5, 0
	v_cvt_pk_bf16_f32 v112, v112, v113
	v_cvt_pk_bf16_f32 v113, v114, v115
	global_store_dwordx2 v153, v[112:113], s[4:5]
	s_sub_u32 s4, s4, 0x18000
	s_subb_u32 s5, s5, 0
	ds_read_b128 v[166:169], v231
	ds_read_b128 v[170:173], v234
	ds_read_b128 v[176:179], v234 offset:4352
	ds_read_b128 v[180:183], v234 offset:8704
	ds_read_b128 v[236:239], v234 offset:13056
	ds_read_b128 v[240:243], v231 offset:64
	s_waitcnt lgkmcnt(4)
	v_mfma_f32_16x16x32_bf16 v[100:103], v[166:169], v[170:173], 0
	ds_read_b128 v[170:173], v234 offset:64
	s_waitcnt lgkmcnt(4)
	v_mfma_f32_16x16x32_bf16 v[104:107], v[166:169], v[176:179], 0
	ds_read_b128 v[176:179], v234 offset:4416
	s_waitcnt lgkmcnt(4)
	v_mfma_f32_16x16x32_bf16 v[108:111], v[166:169], v[180:183], 0
	ds_read_b128 v[180:183], v234 offset:8768
	s_waitcnt lgkmcnt(4)
	v_mfma_f32_16x16x32_bf16 v[112:115], v[166:169], v[236:239], 0
	ds_read_b128 v[166:169], v234 offset:13120
	ds_read_b128 v[236:239], v231 offset:128
	s_waitcnt lgkmcnt(4)
	v_mfma_f32_16x16x32_bf16 v[100:103], v[240:243], v[170:173], v[100:103]
	ds_read_b128 v[170:173], v234 offset:128
	s_waitcnt lgkmcnt(4)
	v_mfma_f32_16x16x32_bf16 v[104:107], v[240:243], v[176:179], v[104:107]
	ds_read_b128 v[176:179], v234 offset:4480
	s_waitcnt lgkmcnt(4)
	v_mfma_f32_16x16x32_bf16 v[108:111], v[240:243], v[180:183], v[108:111]
	ds_read_b128 v[180:183], v234 offset:8832
	s_waitcnt lgkmcnt(4)
	v_mfma_f32_16x16x32_bf16 v[112:115], v[240:243], v[166:169], v[112:115]
	ds_read_b128 v[240:243], v234 offset:13184
	ds_read_b128 v[166:169], v231 offset:192
	s_waitcnt lgkmcnt(4)
	v_mfma_f32_16x16x32_bf16 v[100:103], v[236:239], v[170:173], v[100:103]
	ds_read_b128 v[170:173], v234 offset:192
	s_waitcnt lgkmcnt(4)
	v_mfma_f32_16x16x32_bf16 v[104:107], v[236:239], v[176:179], v[104:107]
	ds_read_b128 v[176:179], v234 offset:4544
	s_waitcnt lgkmcnt(4)
	v_mfma_f32_16x16x32_bf16 v[108:111], v[236:239], v[180:183], v[108:111]
	ds_read_b128 v[180:183], v234 offset:8896
	s_waitcnt lgkmcnt(4)
	v_mfma_f32_16x16x32_bf16 v[112:115], v[236:239], v[240:243], v[112:115]
	ds_read_b128 v[236:239], v234 offset:13248
	ds_read_b128 v[240:243], v235
	s_waitcnt lgkmcnt(4)
	v_mfma_f32_16x16x32_bf16 v[100:103], v[166:169], v[170:173], v[100:103]
	ds_read_b128 v[170:173], v235 offset:2304
	s_waitcnt lgkmcnt(4)
	v_mfma_f32_16x16x32_bf16 v[104:107], v[166:169], v[176:179], v[104:107]
	ds_read_b128 v[176:179], v235 offset:4608
	s_waitcnt lgkmcnt(4)
	v_mfma_f32_16x16x32_bf16 v[108:111], v[166:169], v[180:183], v[108:111]
	ds_read_b128 v[180:183], v235 offset:6912
	s_waitcnt lgkmcnt(4)
	v_mfma_f32_16x16x32_bf16 v[112:115], v[166:169], v[236:239], v[112:115]
	ds_read_b128 v[166:169], v235 offset:64
	ds_read_b128 v[236:239], v235 offset:2368
	s_waitcnt lgkmcnt(5)
	v_mfma_f32_16x16x32_bf16 v[100:103], v[96:99], v[240:243], v[100:103]
	ds_read_b128 v[240:243], v235 offset:4672
	s_waitcnt lgkmcnt(5)
	v_mfma_f32_16x16x32_bf16 v[104:107], v[96:99], v[170:173], v[104:107]
	ds_read_b128 v[170:173], v235 offset:6976
	s_waitcnt lgkmcnt(5)
	v_mfma_f32_16x16x32_bf16 v[108:111], v[96:99], v[176:179], v[108:111]
	s_waitcnt lgkmcnt(4)
	v_mfma_f32_16x16x32_bf16 v[112:115], v[96:99], v[180:183], v[112:115]
	s_waitcnt lgkmcnt(3)
	v_mfma_f32_16x16x32_bf16 v[100:103], v[88:91], v[166:169], v[100:103]
	s_waitcnt lgkmcnt(2)
	v_mfma_f32_16x16x32_bf16 v[104:107], v[88:91], v[236:239], v[104:107]
	s_waitcnt lgkmcnt(1)
	v_mfma_f32_16x16x32_bf16 v[108:111], v[88:91], v[240:243], v[108:111]
	s_waitcnt lgkmcnt(0)
	v_mfma_f32_16x16x32_bf16 v[112:115], v[88:91], v[170:173], v[112:115]
	s_nop 7
	s_and_b64 vcc, exec, s[66:67]
	s_cbranch_vccnz .Lgla_s4_skip1
	s_waitcnt vmcnt(4)
	v_lshlrev_b32_e32 v166, 16, v244
	v_and_b32_e32 v167, 0xffff0000, v244
	v_lshlrev_b32_e32 v168, 16, v245
	v_and_b32_e32 v169, 0xffff0000, v245
	v_pk_add_f32 v[100:101], v[100:101], v[166:167]
	v_pk_add_f32 v[102:103], v[102:103], v[168:169]
	v_lshlrev_b32_e32 v166, 16, v246
	v_and_b32_e32 v167, 0xffff0000, v246
	v_lshlrev_b32_e32 v168, 16, v247
	v_and_b32_e32 v169, 0xffff0000, v247
	v_pk_add_f32 v[104:105], v[104:105], v[166:167]
	v_pk_add_f32 v[106:107], v[106:107], v[168:169]
	v_lshlrev_b32_e32 v166, 16, v250
	v_and_b32_e32 v167, 0xffff0000, v250
	v_lshlrev_b32_e32 v168, 16, v251
	v_and_b32_e32 v169, 0xffff0000, v251
	v_pk_add_f32 v[108:109], v[108:109], v[166:167]
	v_pk_add_f32 v[110:111], v[110:111], v[168:169]
	v_lshlrev_b32_e32 v166, 16, v252
	v_and_b32_e32 v167, 0xffff0000, v252
	v_lshlrev_b32_e32 v168, 16, v253
	v_and_b32_e32 v169, 0xffff0000, v253
	v_pk_add_f32 v[112:113], v[112:113], v[166:167]
	v_pk_add_f32 v[114:115], v[114:115], v[168:169]
.Lgla_s4_skip1:
	v_cvt_pk_bf16_f32 v100, v100, v101
	v_cvt_pk_bf16_f32 v101, v102, v103
	global_store_dwordx2 v153, v[100:101], s[4:5] offset:32
	s_add_u32 s4, s4, 0x8000
	s_addc_u32 s5, s5, 0
	v_cvt_pk_bf16_f32 v104, v104, v105
	v_cvt_pk_bf16_f32 v105, v106, v107
	global_store_dwordx2 v153, v[104:105], s[4:5] offset:32
	s_add_u32 s4, s4, 0x8000
	s_addc_u32 s5, s5, 0
	v_cvt_pk_bf16_f32 v108, v108, v109
	v_cvt_pk_bf16_f32 v109, v110, v111
	global_store_dwordx2 v153, v[108:109], s[4:5] offset:32
	s_add_u32 s4, s4, 0x8000
	s_addc_u32 s5, s5, 0
	v_cvt_pk_bf16_f32 v112, v112, v113
	v_cvt_pk_bf16_f32 v113, v114, v115
	global_store_dwordx2 v153, v[112:113], s[4:5] offset:32
	s_cmp_eq_u32 s68, 7
	s_cbranch_scc1 .LBB0_514
	s_sub_i32 s66, 6, s68
	s_add_i32 s68, s68, 1
	s_and_b64 s[4:5], s[14:15], exec
	s_cselect_b32 s4, s68, s66
	s_lshl_b32 s66, s4, 6
	s_add_i32 s66, s66, s97
	v_add_u32_e32 v166, s66, v189
	v_add_u32_e32 v170, s66, v190
	v_mad_i64_i32 v[166:167], s[4:5], v166, s80, v[140:141]
	v_mad_i64_i32 v[170:171], s[4:5], v170, s80, v[140:141]
	global_load_dwordx4 v[104:107], v[166:167], off
	global_load_dwordx4 v[100:103], v[170:171], off
	s_branch .LBB0_452
